# v28: v26 + one static s_setprio 1 for waves 4-7 around the latent attention K/V loop
# speedup vs baseline: 1.0051x; 1.0051x over previous
.LBB0_747:
	s_and_b64 vcc, exec, s[10:11]
	s_cbranch_vccz .LBB0_751
	v_mov_b32_e32 v10, v232
	s_load_dwordx8 s[52:59], s[44:45], 0x60
	v_and_b32_e32 v181, 63, v10
	v_readlane_b32 s10, v255, 20
	v_mov_b32_e32 v3, v0
	s_load_dwordx2 s[42:43], s[44:45], 0xb0
	v_or_b32_e32 v2, s10, v181
	v_lshlrev_b64 v[2:3], 2, v[2:3]
	s_waitcnt lgkmcnt(0)
	v_lshl_add_u64 v[4:5], s[52:53], 0, v[2:3]
	global_load_dword v11, v[4:5], off
	v_lshl_add_u64 v[4:5], s[54:55], 0, v[2:3]
	global_load_dword v12, v[4:5], off
	v_lshl_add_u64 v[4:5], s[56:57], 0, v[2:3]
	v_lshl_add_u64 v[2:3], s[58:59], 0, v[2:3]
	global_load_dword v13, v[4:5], off
	global_load_dword v14, v[2:3], off
	s_add_i32 s6, s37, s48
	s_lshl_b32 s14, s36, 7
	s_lshl_b32 s30, s36, 8
	v_readlane_b32 s11, v255, 21
	s_add_u32 s10, s42, s47
	s_addc_u32 s11, s43, s46
	s_add_u32 s36, s10, s30
	s_addc_u32 s37, s11, 0
	s_lshl_b32 s10, s27, 10
	s_or_b32 s10, s14, s10
	s_mul_hi_i32 s11, s10, 0x2200
	s_mulk_i32 s10, 0x2200
	v_ashrrev_i32_e32 v50, 4, v10
	s_add_u32 s10, s42, s10
	v_ashrrev_i32_e32 v51, 31, v50
	v_and_b32_e32 v177, 15, v10
	s_addc_u32 s11, s43, s11
	v_lshlrev_b64 v[52:53], 11, v[50:51]
	s_add_u32 s40, s10, 0xe010000
	v_lshl_add_u64 v[2:3], s[36:37], 0, v[52:53]
	v_lshlrev_b32_e32 v124, 4, v177
	v_mov_b32_e32 v125, v0
	s_addc_u32 s41, s11, 0
	v_lshl_add_u64 v[2:3], v[2:3], 0, v[124:125]
	s_mov_b32 s15, 0x16810000
	v_mov_b64_e32 v[4:5], s[40:41]
	s_movk_i32 s35, 0x2200
	v_add_co_u32_e32 v6, vcc, s15, v2
	v_mad_i64_i32 v[4:5], s[36:37], v50, s35, v[4:5]
	s_nop 0
	v_addc_co_u32_e32 v7, vcc, 0, v3, vcc
	s_mov_b32 s15, 0x16820000
	v_lshl_add_u64 v[4:5], v[4:5], 0, v[124:125]
	global_load_dwordx4 v[18:21], v[6:7], off
	global_load_dwordx4 v[22:25], v[4:5], off
	v_add_co_u32_e32 v6, vcc, s15, v2
	s_mov_b32 s15, 0x44000
	s_nop 0
	v_addc_co_u32_e32 v7, vcc, 0, v3, vcc
	v_add_co_u32_e32 v8, vcc, s15, v4
	s_mov_b32 s15, 0x16830000
	s_nop 0
	v_addc_co_u32_e32 v9, vcc, 0, v5, vcc
	global_load_dwordx4 v[26:29], v[6:7], off
	global_load_dwordx4 v[30:33], v[8:9], off
	v_add_co_u32_e32 v6, vcc, s15, v2
	s_mov_b32 s15, 0x88000
	s_nop 0
	v_addc_co_u32_e32 v7, vcc, 0, v3, vcc
	v_add_co_u32_e32 v8, vcc, s15, v4
	s_mov_b32 s15, 0x16840000
	s_nop 0
	v_addc_co_u32_e32 v9, vcc, 0, v5, vcc
	v_add_co_u32_e32 v2, vcc, s15, v2
	s_mov_b32 s15, 0xcc000
	s_nop 0
	v_addc_co_u32_e32 v3, vcc, 0, v3, vcc
	v_add_co_u32_e32 v4, vcc, s15, v4
	global_load_dwordx4 v[34:37], v[6:7], off
	global_load_dwordx4 v[38:41], v[8:9], off
	v_addc_co_u32_e32 v5, vcc, 0, v5, vcc
	global_load_dwordx4 v[42:45], v[2:3], off
	global_load_dwordx4 v[46:49], v[4:5], off
	v_ashrrev_i32_e32 v4, 2, v10
	v_and_b32_e32 v4, 0xffffffe0, v4
	v_add_u32_e32 v180, s6, v4
	v_ashrrev_i32_e32 v182, 6, v10
	v_and_b32_e32 v179, 1, v182
	v_mov_b32_e32 v55, v0
	v_lshlrev_b32_e32 v54, 7, v179
	s_waitcnt vmcnt(10)
	v_mul_f32_e32 v2, v11, v12
	ds_bpermute_b32 v2, v1, v2
	v_and_b32_e32 v56, 48, v10
	v_mov_b32_e32 v57, v0
	s_waitcnt vmcnt(8)
	v_mul_f32_e32 v3, v13, v14
	ds_bpermute_b32 v3, v1, v3
	s_waitcnt lgkmcnt(1)
	v_fmac_f32_e32 v2, v11, v12
	ds_bpermute_b32 v5, v176, v2
	s_mov_b32 s6, 0x14610000
	s_mov_b64 s[36:37], 0x14610000
	s_waitcnt lgkmcnt(1)
	v_fmac_f32_e32 v3, v13, v14
	ds_bpermute_b32 v6, v176, v3
	s_waitcnt lgkmcnt(1)
	v_add_f32_e32 v4, v2, v5
	v_or_b32_e32 v2, v180, v177
	v_bfe_u32 v178, v10, 4, 2
	v_lshlrev_b32_e32 v51, 2, v50
	s_waitcnt lgkmcnt(0)
	v_add_f32_e32 v5, v3, v6
	ds_bpermute_b32 v6, v175, v4
	ds_bpermute_b32 v7, v175, v5
	v_ashrrev_i32_e32 v3, 31, v2
	v_lshlrev_b64 v[2:3], 11, v[2:3]
	v_lshl_add_u64 v[2:3], s[42:43], 0, v[2:3]
	s_waitcnt lgkmcnt(1)
	v_add_f32_e32 v4, v4, v6
	s_waitcnt lgkmcnt(0)
	v_add_f32_e32 v5, v5, v7
	ds_bpermute_b32 v6, v174, v4
	ds_bpermute_b32 v7, v174, v5
	v_lshl_add_u64 v[2:3], v[2:3], 0, s[30:31]
	v_lshl_add_u64 v[2:3], v[2:3], 0, v[54:55]
	v_lshrrev_b32_e32 v55, 1, v50
	s_waitcnt lgkmcnt(1)
	v_add_f32_e32 v132, v4, v6
	s_waitcnt lgkmcnt(0)
	v_add_f32_e32 v133, v5, v7
	v_lshl_add_u64 v[6:7], v[2:3], 0, v[56:57]
	v_add_co_u32_e32 v4, vcc, s6, v6
	s_mov_b32 s6, 0x14618000
	s_nop 0
	v_addc_co_u32_e32 v5, vcc, 0, v7, vcc
	v_lshl_add_u64 v[2:3], v[6:7], 0, s[36:37]
	v_add_co_u32_e32 v6, vcc, s6, v6
	global_load_dwordx4 v[10:13], v[4:5], off
	s_nop 0
	global_load_dwordx4 v[2:5], v[2:3], off offset:64
	v_addc_co_u32_e32 v7, vcc, 0, v7, vcc
	global_load_dwordx4 v[14:17], v[6:7], off
	s_nop 0
	global_load_dwordx4 v[6:9], v[6:7], off offset:64
	v_and_b32_e32 v51, 16, v51
	v_and_b32_e32 v55, 12, v55
	v_and_b32_e32 v57, 0xfffffe3, v50
	v_or3_b32 v51, v57, v51, v55
	s_movk_i32 s6, 0x110
	v_mul_lo_u32 v55, v50, s6
	v_mad_u64_u32 v[126:127], s[36:37], v51, s6, v[124:125]
	s_mov_b32 s6, 0x11000
	v_add3_u32 v127, v55, v124, s6
	v_add_u32_e32 v51, 0, v126
	v_add_u32_e32 v55, 0, v127
	s_waitcnt vmcnt(11)
	ds_write_b128 v51, v[18:21]
	s_waitcnt vmcnt(10)
	ds_write_b128 v55, v[22:25]
	s_waitcnt vmcnt(9)
	ds_write_b128 v51, v[26:29] offset:8704
	s_waitcnt vmcnt(8)
	ds_write_b128 v55, v[30:33] offset:8704
	s_waitcnt vmcnt(7)
	ds_write_b128 v51, v[34:37] offset:17408
	s_waitcnt vmcnt(6)
	ds_write_b128 v55, v[38:41] offset:17408
	s_waitcnt vmcnt(5)
	ds_write_b128 v51, v[42:45] offset:26112
	s_waitcnt vmcnt(4)
	ds_write_b128 v55, v[46:49] offset:26112
	s_add_i32 s6, 0, 0x11000
	v_mul_u32_u24_e32 v19, 0x110, v177
	v_add3_u32 v183, s6, v56, v19
	s_lshl_b32 s6, s26, 3
	s_and_b32 s6, s6, 0x700
	ds_bpermute_b32 v134, v173, v132
	ds_bpermute_b32 v135, v173, v133
	s_add_u32 s6, s42, s6
	v_add_u32_e32 v18, 0, v54
	s_addc_u32 s18, s43, 0
	v_add3_u32 v137, v18, v56, v19
	s_add_u32 s26, s6, s47
	v_mov_b64_e32 v[18:19], s[10:11]
	s_addc_u32 s27, s18, s46
	v_mad_i64_i32 v[130:131], s[10:11], v50, s35, v[18:19]
	v_mov_b32_e32 v18, 0
	s_mov_b32 s15, 0
	v_lshl_add_u64 v[128:129], s[26:27], 0, v[52:53]
	v_mov_b32_e32 v19, v18
	v_mov_b32_e32 v20, v18
	v_mov_b32_e32 v21, v18
	v_mov_b32_e32 v22, v18
	v_mov_b32_e32 v23, v18
	v_mov_b32_e32 v24, v18
	v_mov_b32_e32 v25, v18
	v_mov_b32_e32 v26, v18
	v_mov_b32_e32 v27, v18
	v_mov_b32_e32 v28, v18
	v_mov_b32_e32 v29, v18
	v_mov_b32_e32 v30, v18
	v_mov_b32_e32 v31, v18
	v_mov_b32_e32 v32, v18
	v_mov_b32_e32 v33, v18
	v_mov_b32_e32 v38, v18
	v_mov_b32_e32 v39, v18
	v_mov_b32_e32 v40, v18
	v_mov_b32_e32 v41, v18
	v_mov_b32_e32 v46, v18
	v_mov_b32_e32 v47, v18
	v_mov_b32_e32 v48, v18
	v_mov_b32_e32 v49, v18
	v_mov_b32_e32 v62, v18
	v_mov_b32_e32 v63, v18
	v_mov_b32_e32 v64, v18
	v_mov_b32_e32 v65, v18
	v_mov_b32_e32 v74, v18
	v_mov_b32_e32 v75, v18
	v_mov_b32_e32 v76, v18
	v_mov_b32_e32 v77, v18
	v_mov_b32_e32 v34, v18
	v_mov_b32_e32 v35, v18
	v_mov_b32_e32 v36, v18
	v_mov_b32_e32 v37, v18
	v_mov_b32_e32 v42, v18
	v_mov_b32_e32 v43, v18
	v_mov_b32_e32 v44, v18
	v_mov_b32_e32 v45, v18
	v_mov_b32_e32 v50, v18
	v_mov_b32_e32 v51, v18
	v_mov_b32_e32 v52, v18
	v_mov_b32_e32 v53, v18
	v_mov_b32_e32 v54, v18
	v_mov_b32_e32 v55, v18
	v_mov_b32_e32 v56, v18
	v_mov_b32_e32 v57, v18
	v_mov_b32_e32 v58, v18
	v_mov_b32_e32 v59, v18
	v_mov_b32_e32 v60, v18
	v_mov_b32_e32 v61, v18
	v_mov_b32_e32 v66, v18
	v_mov_b32_e32 v67, v18
	v_mov_b32_e32 v68, v18
	v_mov_b32_e32 v69, v18
	v_mov_b32_e32 v70, v18
	v_mov_b32_e32 v71, v18
	v_mov_b32_e32 v72, v18
	v_mov_b32_e32 v73, v18
	v_mov_b32_e32 v78, v18
	v_mov_b32_e32 v79, v18
	v_mov_b32_e32 v80, v18
	v_mov_b32_e32 v81, v18
	v_mov_b32_e32 v122, v18
	v_mov_b32_e32 v123, v18
	s_mov_b32 s11, 0xe054000
	s_mov_b32 s18, 0x16870000
	s_mov_b32 s26, 0xe098000
	s_mov_b32 s27, 0x16880000
	s_mov_b32 s30, 0xe0dc000
	s_mov_b64 s[36:37], 0x40000
	s_waitcnt lgkmcnt(0)
	s_barrier
	s_waitcnt vmcnt(0) lgkmcnt(0)
	v_writelane_b32 v175, s64, 0
	v_writelane_b32 v175, s65, 1
	v_writelane_b32 v175, s66, 2
	v_writelane_b32 v175, s67, 3
	v_writelane_b32 v175, s68, 4
	v_writelane_b32 v175, s69, 5
	v_writelane_b32 v175, s70, 6
	v_writelane_b32 v175, s71, 7
	v_writelane_b32 v175, s72, 8
	v_writelane_b32 v175, s73, 9
	v_writelane_b32 v175, s74, 10
	v_writelane_b32 v175, s75, 11
	v_writelane_b32 v175, s76, 12
	v_writelane_b32 v175, s77, 13
	v_writelane_b32 v175, s78, 14
	v_writelane_b32 v175, s79, 15
	v_lshl_add_u64 v[138:139], v[128:129], 0, v[124:125]
	v_lshl_add_u64 v[140:141], v[130:131], 0, v[124:125]
	s_nop 1
	v_readfirstlane_b32 s64, v138
	v_readfirstlane_b32 s65, v139
	v_readfirstlane_b32 s72, v140
	v_readfirstlane_b32 s73, v141
	s_nop 3
	v_subrev_u32_e32 v124, s64, v138
	v_subrev_u32_e32 v125, s72, v140
	s_add_u32 s66, s64, s97
	s_addc_u32 s67, s65, 0
	s_add_u32 s68, s64, s18
	s_addc_u32 s69, s65, 0
	s_add_u32 s70, s64, s27
	s_addc_u32 s71, s65, 0
	s_add_u32 s64, s64, s96
	s_addc_u32 s65, s65, 0
	s_add_u32 s74, s72, s11
	s_addc_u32 s75, s73, 0
	s_add_u32 s74, s74, 0x100
	s_addc_u32 s75, s75, 0
	s_add_u32 s76, s72, s26
	s_addc_u32 s77, s73, 0
	s_add_u32 s76, s76, 0x100
	s_addc_u32 s77, s77, 0
	s_add_u32 s78, s72, s30
	s_addc_u32 s79, s73, 0
	s_add_u32 s78, s78, 0x100
	s_addc_u32 s79, s79, 0
	s_add_u32 s72, s72, s91
	s_addc_u32 s73, s73, 0
	s_add_u32 s72, s72, 0x100
	s_addc_u32 s73, s73, 0
	s_mov_b32 s15, 0
	s_nop 4
	v_readfirstlane_b32 s100, v232
	s_nop 3
	s_lshr_b32 s100, s100, 6
	s_cmp_ge_u32 s100, 4
	s_cbranch_scc0 .Lattn_prio_done
	s_setprio 1
.Lattn_prio_done:
.Lattn_nf_loop:
	s_and_b32 s10, s15, 1
	s_mul_i32 s6, s10, 0x8800
	v_add_u32_e32 v136, s6, v137
	v_add_u32_e32 v170, s6, v183
	s_sub_u32 s10, 0x8800, s6
	ds_read_b128 v[98:101], v136 offset:0
	ds_read_b128 v[102:105], v136 offset:64
	ds_read_b128 v[106:109], v136 offset:4352
	ds_read_b128 v[110:113], v136 offset:4416
	v_add_u32_e32 v171, s10, v126
	v_add_u32_e32 v173, s10, v127
	global_load_dwordx4 v[82:85], v124, s[64:65]
	global_load_dwordx4 v[86:89], v124, s[66:67]
	global_load_dwordx4 v[90:93], v124, s[68:69]
	global_load_dwordx4 v[94:97], v124, s[70:71]
	v_add_u32_e32 v124, s36, v124
	s_waitcnt lgkmcnt(3)
	v_mfma_f32_16x16x32_bf16 v[138:141], v[98:101], v[10:13], 0
	v_mfma_f32_16x16x32_bf16 v[142:145], v[98:101], v[14:17], 0
	s_waitcnt lgkmcnt(2)
	v_mfma_f32_16x16x32_bf16 v[138:141], v[102:105], v[2:5], v[138:141]
	v_mfma_f32_16x16x32_bf16 v[142:145], v[102:105], v[6:9], v[142:145]
	ds_read_b128 v[98:101], v136 offset:8704
	ds_read_b128 v[102:105], v136 offset:8768
	s_waitcnt lgkmcnt(3)
	v_mfma_f32_16x16x32_bf16 v[146:149], v[106:109], v[10:13], 0
	v_mfma_f32_16x16x32_bf16 v[150:153], v[106:109], v[14:17], 0
	s_waitcnt lgkmcnt(2)
	v_mfma_f32_16x16x32_bf16 v[146:149], v[110:113], v[2:5], v[146:149]
	v_mfma_f32_16x16x32_bf16 v[150:153], v[110:113], v[6:9], v[150:153]
	ds_read_b128 v[106:109], v136 offset:13056
	ds_read_b128 v[110:113], v136 offset:13120
	v_exp_f32_e32 v138, v138
	v_exp_f32_e32 v139, v139
	v_exp_f32_e32 v140, v140
	v_exp_f32_e32 v141, v141
	v_exp_f32_e32 v142, v142
	v_exp_f32_e32 v143, v143
	v_exp_f32_e32 v144, v144
	v_exp_f32_e32 v145, v145
	v_add_f32_e32 v123, v138, v123
	v_add_f32_e32 v122, v142, v122
	v_add_f32_e32 v123, v139, v123
	v_add_f32_e32 v122, v143, v122
	v_add_f32_e32 v123, v140, v123
	v_add_f32_e32 v122, v144, v122
	v_add_f32_e32 v123, v141, v123
	v_add_f32_e32 v122, v145, v122
	s_waitcnt lgkmcnt(3)
	v_mfma_f32_16x16x32_bf16 v[154:157], v[98:101], v[10:13], 0
	v_exp_f32_e32 v146, v146
	v_exp_f32_e32 v147, v147
	v_mfma_f32_16x16x32_bf16 v[158:161], v[98:101], v[14:17], 0
	v_exp_f32_e32 v148, v148
	v_exp_f32_e32 v149, v149
	s_waitcnt lgkmcnt(2)
	v_mfma_f32_16x16x32_bf16 v[154:157], v[102:105], v[2:5], v[154:157]
	v_exp_f32_e32 v150, v150
	v_exp_f32_e32 v151, v151
	v_mfma_f32_16x16x32_bf16 v[158:161], v[102:105], v[6:9], v[158:161]
	v_exp_f32_e32 v152, v152
	v_exp_f32_e32 v153, v153
	v_cvt_pk_bf16_f32 v114, v138, v139
	v_cvt_pk_bf16_f32 v115, v140, v141
	v_cvt_pk_bf16_f32 v118, v142, v143
	v_cvt_pk_bf16_f32 v119, v144, v145
	ds_read_b128 v[138:141], v170 offset:0
	ds_read_b128 v[142:145], v170 offset:4352
	s_waitcnt lgkmcnt(3)
	v_mfma_f32_16x16x32_bf16 v[162:165], v[106:109], v[10:13], 0
	v_add_f32_e32 v123, v146, v123
	v_add_f32_e32 v122, v150, v122
	v_add_f32_e32 v123, v147, v123
	v_mfma_f32_16x16x32_bf16 v[166:169], v[106:109], v[14:17], 0
	v_add_f32_e32 v122, v151, v122
	v_add_f32_e32 v123, v148, v123
	v_add_f32_e32 v122, v152, v122
	s_waitcnt lgkmcnt(2)
	v_mfma_f32_16x16x32_bf16 v[162:165], v[110:113], v[2:5], v[162:165]
	v_add_f32_e32 v123, v149, v123
	v_add_f32_e32 v122, v153, v122
	v_cvt_pk_bf16_f32 v116, v146, v147
	v_cvt_pk_bf16_f32 v117, v148, v149
	v_mfma_f32_16x16x32_bf16 v[166:169], v[110:113], v[6:9], v[166:169]
	v_cvt_pk_bf16_f32 v120, v150, v151
	v_cvt_pk_bf16_f32 v121, v152, v153
	ds_read_b128 v[146:149], v170 offset:8704
	ds_read_b128 v[150:153], v170 offset:13056
	ds_read_b128 v[98:101], v170 offset:17408
	ds_read_b128 v[102:105], v170 offset:21760
	ds_read_b128 v[106:109], v170 offset:26112
	ds_read_b128 v[110:113], v170 offset:30464
	v_exp_f32_e32 v154, v154
	v_exp_f32_e32 v155, v155
	v_exp_f32_e32 v156, v156
	v_exp_f32_e32 v157, v157
	v_exp_f32_e32 v158, v158
	v_exp_f32_e32 v159, v159
	v_exp_f32_e32 v160, v160
	v_exp_f32_e32 v161, v161
	s_waitcnt lgkmcnt(7)
	v_mfma_f32_16x16x32_bf16 v[78:81], v[138:141], v[114:117], v[78:81]
	v_mfma_f32_16x16x32_bf16 v[74:77], v[138:141], v[118:121], v[74:77]
	v_exp_f32_e32 v162, v162
	v_exp_f32_e32 v163, v163
	v_exp_f32_e32 v164, v164
	v_exp_f32_e32 v165, v165
	s_waitcnt lgkmcnt(6)
	v_mfma_f32_16x16x32_bf16 v[70:73], v[142:145], v[114:117], v[70:73]
	v_mfma_f32_16x16x32_bf16 v[62:65], v[142:145], v[118:121], v[62:65]
	v_exp_f32_e32 v166, v166
	v_exp_f32_e32 v167, v167
	v_exp_f32_e32 v168, v168
	v_exp_f32_e32 v169, v169
	s_waitcnt lgkmcnt(5)
	v_mfma_f32_16x16x32_bf16 v[66:69], v[146:149], v[114:117], v[66:69]
	v_mfma_f32_16x16x32_bf16 v[46:49], v[146:149], v[118:121], v[46:49]
	v_add_f32_e32 v123, v154, v123
	v_add_f32_e32 v122, v158, v122
	v_add_f32_e32 v123, v155, v123
	v_add_f32_e32 v122, v159, v122
	v_add_f32_e32 v123, v156, v123
	v_add_f32_e32 v122, v160, v122
	v_add_f32_e32 v123, v157, v123
	v_add_f32_e32 v122, v161, v122
	s_waitcnt lgkmcnt(4)
	v_mfma_f32_16x16x32_bf16 v[58:61], v[150:153], v[114:117], v[58:61]
	v_mfma_f32_16x16x32_bf16 v[38:41], v[150:153], v[118:121], v[38:41]
	ds_read_b128 v[138:141], v170 offset:17472
	ds_read_b128 v[142:145], v170 offset:21824
	ds_read_b128 v[146:149], v170 offset:26176
	ds_read_b128 v[150:153], v170 offset:30528
	v_cvt_pk_bf16_f32 v184, v154, v155
	v_cvt_pk_bf16_f32 v185, v156, v157
	v_cvt_pk_bf16_f32 v128, v158, v159
	v_cvt_pk_bf16_f32 v129, v160, v161
	s_waitcnt lgkmcnt(7)
	v_mfma_f32_16x16x32_bf16 v[54:57], v[98:101], v[114:117], v[54:57]
	v_mfma_f32_16x16x32_bf16 v[30:33], v[98:101], v[118:121], v[30:33]
	v_add_f32_e32 v123, v162, v123
	v_add_f32_e32 v122, v166, v122
	v_add_f32_e32 v123, v163, v123
	v_add_f32_e32 v122, v167, v122
	v_add_f32_e32 v123, v164, v123
	v_add_f32_e32 v122, v168, v122
	v_add_f32_e32 v123, v165, v123
	v_add_f32_e32 v122, v169, v122
	s_waitcnt lgkmcnt(6)
	v_mfma_f32_16x16x32_bf16 v[50:53], v[102:105], v[114:117], v[50:53]
	v_mfma_f32_16x16x32_bf16 v[26:29], v[102:105], v[118:121], v[26:29]
	v_cvt_pk_bf16_f32 v186, v162, v163
	v_cvt_pk_bf16_f32 v187, v164, v165
	v_cvt_pk_bf16_f32 v130, v166, v167
	v_cvt_pk_bf16_f32 v131, v168, v169
	ds_read_b128 v[154:157], v170 offset:64
	ds_read_b128 v[158:161], v170 offset:4416
	ds_read_b128 v[162:165], v170 offset:8768
	ds_read_b128 v[166:169], v170 offset:13120
	s_waitcnt lgkmcnt(9)
	v_mfma_f32_16x16x32_bf16 v[42:45], v[106:109], v[114:117], v[42:45]
	v_mfma_f32_16x16x32_bf16 v[22:25], v[106:109], v[118:121], v[22:25]
	s_waitcnt lgkmcnt(8)
	v_mfma_f32_16x16x32_bf16 v[34:37], v[110:113], v[114:117], v[34:37]
	v_mfma_f32_16x16x32_bf16 v[18:21], v[110:113], v[118:121], v[18:21]
	ds_read_b128 v[98:101], v136 offset:17408
	ds_read_b128 v[102:105], v136 offset:17472
	ds_read_b128 v[106:109], v136 offset:21760
	ds_read_b128 v[110:113], v136 offset:21824
	s_waitcnt lgkmcnt(7)
	v_mfma_f32_16x16x32_bf16 v[78:81], v[154:157], v[184:187], v[78:81]
	v_mfma_f32_16x16x32_bf16 v[74:77], v[154:157], v[128:131], v[74:77]
	s_waitcnt lgkmcnt(6)
	v_mfma_f32_16x16x32_bf16 v[70:73], v[158:161], v[184:187], v[70:73]
	v_mfma_f32_16x16x32_bf16 v[62:65], v[158:161], v[128:131], v[62:65]
	s_waitcnt vmcnt(3)
	ds_write_b128 v171, v[82:85] offset:0
	s_waitcnt vmcnt(2)
	ds_write_b128 v171, v[86:89] offset:8704
	s_waitcnt vmcnt(1)
	ds_write_b128 v171, v[90:93] offset:17408
	s_waitcnt vmcnt(0)
	ds_write_b128 v171, v[94:97] offset:26112
	s_waitcnt lgkmcnt(9)
	v_mfma_f32_16x16x32_bf16 v[66:69], v[162:165], v[184:187], v[66:69]
	v_mfma_f32_16x16x32_bf16 v[46:49], v[162:165], v[128:131], v[46:49]
	s_waitcnt lgkmcnt(8)
	v_mfma_f32_16x16x32_bf16 v[58:61], v[166:169], v[184:187], v[58:61]
	v_mfma_f32_16x16x32_bf16 v[38:41], v[166:169], v[128:131], v[38:41]
	global_load_dwordx4 v[82:85], v125, s[72:73]
	global_load_dwordx4 v[86:89], v125, s[74:75]
	global_load_dwordx4 v[90:93], v125, s[76:77]
	global_load_dwordx4 v[94:97], v125, s[78:79]
	v_add_u32_e32 v125, s38, v125
	v_mfma_f32_16x16x32_bf16 v[54:57], v[138:141], v[184:187], v[54:57]
	v_mfma_f32_16x16x32_bf16 v[30:33], v[138:141], v[128:131], v[30:33]
	v_mfma_f32_16x16x32_bf16 v[50:53], v[142:145], v[184:187], v[50:53]
	v_mfma_f32_16x16x32_bf16 v[26:29], v[142:145], v[128:131], v[26:29]
	v_mfma_f32_16x16x32_bf16 v[42:45], v[146:149], v[184:187], v[42:45]
	v_mfma_f32_16x16x32_bf16 v[22:25], v[146:149], v[128:131], v[22:25]
	v_mfma_f32_16x16x32_bf16 v[34:37], v[150:153], v[184:187], v[34:37]
	v_mfma_f32_16x16x32_bf16 v[18:21], v[150:153], v[128:131], v[18:21]
	s_waitcnt lgkmcnt(7)
	v_mfma_f32_16x16x32_bf16 v[138:141], v[98:101], v[10:13], 0
	v_mfma_f32_16x16x32_bf16 v[142:145], v[98:101], v[14:17], 0
	s_waitcnt lgkmcnt(6)
	v_mfma_f32_16x16x32_bf16 v[138:141], v[102:105], v[2:5], v[138:141]
	v_mfma_f32_16x16x32_bf16 v[142:145], v[102:105], v[6:9], v[142:145]
	ds_read_b128 v[98:101], v136 offset:26112
	ds_read_b128 v[102:105], v136 offset:26176
	s_waitcnt lgkmcnt(7)
	v_mfma_f32_16x16x32_bf16 v[146:149], v[106:109], v[10:13], 0
	v_mfma_f32_16x16x32_bf16 v[150:153], v[106:109], v[14:17], 0
	s_waitcnt lgkmcnt(6)
	v_mfma_f32_16x16x32_bf16 v[146:149], v[110:113], v[2:5], v[146:149]
	v_mfma_f32_16x16x32_bf16 v[150:153], v[110:113], v[6:9], v[150:153]
	ds_read_b128 v[106:109], v136 offset:30464
	ds_read_b128 v[110:113], v136 offset:30528
	v_exp_f32_e32 v138, v138
	v_exp_f32_e32 v139, v139
	v_exp_f32_e32 v140, v140
	v_exp_f32_e32 v141, v141
	v_exp_f32_e32 v142, v142
	v_exp_f32_e32 v143, v143
	v_exp_f32_e32 v144, v144
	v_exp_f32_e32 v145, v145
	v_add_f32_e32 v123, v138, v123
	v_add_f32_e32 v122, v142, v122
	v_add_f32_e32 v123, v139, v123
	v_add_f32_e32 v122, v143, v122
	v_add_f32_e32 v123, v140, v123
	v_add_f32_e32 v122, v144, v122
	v_add_f32_e32 v123, v141, v123
	v_add_f32_e32 v122, v145, v122
	s_waitcnt lgkmcnt(3)
	v_mfma_f32_16x16x32_bf16 v[154:157], v[98:101], v[10:13], 0
	v_exp_f32_e32 v146, v146
	v_exp_f32_e32 v147, v147
	v_mfma_f32_16x16x32_bf16 v[158:161], v[98:101], v[14:17], 0
	v_exp_f32_e32 v148, v148
	v_exp_f32_e32 v149, v149
	s_waitcnt lgkmcnt(2)
	v_mfma_f32_16x16x32_bf16 v[154:157], v[102:105], v[2:5], v[154:157]
	v_exp_f32_e32 v150, v150
	v_exp_f32_e32 v151, v151
	v_mfma_f32_16x16x32_bf16 v[158:161], v[102:105], v[6:9], v[158:161]
	v_exp_f32_e32 v152, v152
	v_exp_f32_e32 v153, v153
	v_cvt_pk_bf16_f32 v114, v138, v139
	v_cvt_pk_bf16_f32 v115, v140, v141
	v_cvt_pk_bf16_f32 v118, v142, v143
	v_cvt_pk_bf16_f32 v119, v144, v145
	ds_read_b128 v[138:141], v170 offset:128
	ds_read_b128 v[142:145], v170 offset:4480
	s_waitcnt lgkmcnt(3)
	v_mfma_f32_16x16x32_bf16 v[162:165], v[106:109], v[10:13], 0
	v_add_f32_e32 v123, v146, v123
	v_add_f32_e32 v122, v150, v122
	v_add_f32_e32 v123, v147, v123
	v_mfma_f32_16x16x32_bf16 v[166:169], v[106:109], v[14:17], 0
	v_add_f32_e32 v122, v151, v122
	v_add_f32_e32 v123, v148, v123
	v_add_f32_e32 v122, v152, v122
	s_waitcnt lgkmcnt(2)
	v_mfma_f32_16x16x32_bf16 v[162:165], v[110:113], v[2:5], v[162:165]
	v_add_f32_e32 v123, v149, v123
	v_add_f32_e32 v122, v153, v122
	v_cvt_pk_bf16_f32 v116, v146, v147
	v_cvt_pk_bf16_f32 v117, v148, v149
	v_mfma_f32_16x16x32_bf16 v[166:169], v[110:113], v[6:9], v[166:169]
	v_cvt_pk_bf16_f32 v120, v150, v151
	v_cvt_pk_bf16_f32 v121, v152, v153
	ds_read_b128 v[146:149], v170 offset:8832
	ds_read_b128 v[150:153], v170 offset:13184
	ds_read_b128 v[98:101], v170 offset:17536
	ds_read_b128 v[102:105], v170 offset:21888
	ds_read_b128 v[106:109], v170 offset:26240
	ds_read_b128 v[110:113], v170 offset:30592
	v_exp_f32_e32 v154, v154
	v_exp_f32_e32 v155, v155
	v_exp_f32_e32 v156, v156
	v_exp_f32_e32 v157, v157
	v_exp_f32_e32 v158, v158
	v_exp_f32_e32 v159, v159
	v_exp_f32_e32 v160, v160
	v_exp_f32_e32 v161, v161
	s_waitcnt lgkmcnt(7)
	v_mfma_f32_16x16x32_bf16 v[78:81], v[138:141], v[114:117], v[78:81]
	v_mfma_f32_16x16x32_bf16 v[74:77], v[138:141], v[118:121], v[74:77]
	v_exp_f32_e32 v162, v162
	v_exp_f32_e32 v163, v163
	v_exp_f32_e32 v164, v164
	v_exp_f32_e32 v165, v165
	s_waitcnt lgkmcnt(6)
	v_mfma_f32_16x16x32_bf16 v[70:73], v[142:145], v[114:117], v[70:73]
	v_mfma_f32_16x16x32_bf16 v[62:65], v[142:145], v[118:121], v[62:65]
	v_exp_f32_e32 v166, v166
	v_exp_f32_e32 v167, v167
	v_exp_f32_e32 v168, v168
	v_exp_f32_e32 v169, v169
	s_waitcnt lgkmcnt(5)
	v_mfma_f32_16x16x32_bf16 v[66:69], v[146:149], v[114:117], v[66:69]
	v_mfma_f32_16x16x32_bf16 v[46:49], v[146:149], v[118:121], v[46:49]
	v_add_f32_e32 v123, v154, v123
	v_add_f32_e32 v122, v158, v122
	v_add_f32_e32 v123, v155, v123
	v_add_f32_e32 v122, v159, v122
	v_add_f32_e32 v123, v156, v123
	v_add_f32_e32 v122, v160, v122
	v_add_f32_e32 v123, v157, v123
	v_add_f32_e32 v122, v161, v122
	s_waitcnt lgkmcnt(4)
	v_mfma_f32_16x16x32_bf16 v[58:61], v[150:153], v[114:117], v[58:61]
	v_mfma_f32_16x16x32_bf16 v[38:41], v[150:153], v[118:121], v[38:41]
	ds_read_b128 v[138:141], v170 offset:17600
	ds_read_b128 v[142:145], v170 offset:21952
	ds_read_b128 v[146:149], v170 offset:26304
	ds_read_b128 v[150:153], v170 offset:30656
	v_cvt_pk_bf16_f32 v184, v154, v155
	v_cvt_pk_bf16_f32 v185, v156, v157
	v_cvt_pk_bf16_f32 v128, v158, v159
	v_cvt_pk_bf16_f32 v129, v160, v161
	s_waitcnt lgkmcnt(7)
	v_mfma_f32_16x16x32_bf16 v[54:57], v[98:101], v[114:117], v[54:57]
	v_mfma_f32_16x16x32_bf16 v[30:33], v[98:101], v[118:121], v[30:33]
	v_add_f32_e32 v123, v162, v123
	v_add_f32_e32 v122, v166, v122
	v_add_f32_e32 v123, v163, v123
	v_add_f32_e32 v122, v167, v122
	v_add_f32_e32 v123, v164, v123
	v_add_f32_e32 v122, v168, v122
	v_add_f32_e32 v123, v165, v123
	v_add_f32_e32 v122, v169, v122
	s_waitcnt lgkmcnt(6)
	v_mfma_f32_16x16x32_bf16 v[50:53], v[102:105], v[114:117], v[50:53]
	v_mfma_f32_16x16x32_bf16 v[26:29], v[102:105], v[118:121], v[26:29]
	v_cvt_pk_bf16_f32 v186, v162, v163
	v_cvt_pk_bf16_f32 v187, v164, v165
	v_cvt_pk_bf16_f32 v130, v166, v167
	v_cvt_pk_bf16_f32 v131, v168, v169
	ds_read_b128 v[154:157], v170 offset:192
	ds_read_b128 v[158:161], v170 offset:4544
	ds_read_b128 v[162:165], v170 offset:8896
	ds_read_b128 v[166:169], v170 offset:13248
	s_waitcnt lgkmcnt(9)
	v_mfma_f32_16x16x32_bf16 v[42:45], v[106:109], v[114:117], v[42:45]
	v_mfma_f32_16x16x32_bf16 v[22:25], v[106:109], v[118:121], v[22:25]
	s_waitcnt lgkmcnt(8)
	v_mfma_f32_16x16x32_bf16 v[34:37], v[110:113], v[114:117], v[34:37]
	v_mfma_f32_16x16x32_bf16 v[18:21], v[110:113], v[118:121], v[18:21]
	s_waitcnt lgkmcnt(3)
	v_mfma_f32_16x16x32_bf16 v[78:81], v[154:157], v[184:187], v[78:81]
	v_mfma_f32_16x16x32_bf16 v[74:77], v[154:157], v[128:131], v[74:77]
	s_waitcnt lgkmcnt(2)
	v_mfma_f32_16x16x32_bf16 v[70:73], v[158:161], v[184:187], v[70:73]
	v_mfma_f32_16x16x32_bf16 v[62:65], v[158:161], v[128:131], v[62:65]
	s_waitcnt lgkmcnt(1)
	v_mfma_f32_16x16x32_bf16 v[66:69], v[162:165], v[184:187], v[66:69]
	v_mfma_f32_16x16x32_bf16 v[46:49], v[162:165], v[128:131], v[46:49]
	s_waitcnt lgkmcnt(0)
	v_mfma_f32_16x16x32_bf16 v[58:61], v[166:169], v[184:187], v[58:61]
	v_mfma_f32_16x16x32_bf16 v[38:41], v[166:169], v[128:131], v[38:41]
	s_waitcnt vmcnt(3)
	ds_write_b128 v173, v[82:85] offset:0
	s_waitcnt vmcnt(2)
	ds_write_b128 v173, v[86:89] offset:8704
	s_waitcnt vmcnt(1)
	ds_write_b128 v173, v[90:93] offset:17408
	s_waitcnt vmcnt(0)
	ds_write_b128 v173, v[94:97] offset:26112
	v_mfma_f32_16x16x32_bf16 v[54:57], v[138:141], v[184:187], v[54:57]
	v_mfma_f32_16x16x32_bf16 v[30:33], v[138:141], v[128:131], v[30:33]
	v_mfma_f32_16x16x32_bf16 v[50:53], v[142:145], v[184:187], v[50:53]
	v_mfma_f32_16x16x32_bf16 v[26:29], v[142:145], v[128:131], v[26:29]
	v_mfma_f32_16x16x32_bf16 v[42:45], v[146:149], v[184:187], v[42:45]
	v_mfma_f32_16x16x32_bf16 v[22:25], v[146:149], v[128:131], v[22:25]
	v_mfma_f32_16x16x32_bf16 v[34:37], v[150:153], v[184:187], v[34:37]
	v_mfma_f32_16x16x32_bf16 v[18:21], v[150:153], v[128:131], v[18:21]
	s_waitcnt lgkmcnt(0)
	s_barrier
	s_add_i32 s15, s15, 1
	s_cmp_eq_u32 s15, 33
	s_cbranch_scc0 .Lattn_nf_loop
	s_setprio 0
	v_readlane_b32 s64, v175, 0
	v_readlane_b32 s65, v175, 1
	v_readlane_b32 s66, v175, 2
	v_readlane_b32 s67, v175, 3
	v_readlane_b32 s68, v175, 4
	v_readlane_b32 s69, v175, 5
	v_readlane_b32 s70, v175, 6
	v_readlane_b32 s71, v175, 7
	v_readlane_b32 s72, v175, 8
	v_readlane_b32 s73, v175, 9
	v_readlane_b32 s74, v175, 10
	v_readlane_b32 s75, v175, 11
	v_readlane_b32 s76, v175, 12
	v_readlane_b32 s77, v175, 13
	v_readlane_b32 s78, v175, 14
	v_readlane_b32 s79, v175, 15
	s_nop 4
	ds_read_b128 v[82:85], v137 offset:34816
	ds_read_b128 v[90:93], v137 offset:34880
	v_add_f32_e32 v186, v132, v134
	v_add_f32_e32 v184, v133, v135
	ds_bpermute_b32 v187, v172, v186
	ds_bpermute_b32 v185, v172, v184
	s_mov_b32 s10, 0x3fb8aa3b
	s_mov_b32 s11, 0xc2ce8ed0
	s_mov_b32 s6, 0x42b17218
	s_waitcnt lgkmcnt(3)
	v_mfma_f32_16x16x32_bf16 v[86:89], v[82:85], v[10:13], 0
	v_cmp_eq_u32_e64 s[40:41], 0, v179
	s_lshl_b32 s30, s14, 1
	v_lshlrev_b32_e32 v196, 3, v178
	v_mov_b32_e32 v197, 0
	v_lshlrev_b32_e32 v198, 4, v179
	v_or3_b32 v198, v198, v177, v180
	v_ashrrev_i32_e32 v199, 31, v198
	v_lshlrev_b64 v[198:199], 11, v[198:199]
	s_mov_b64 s[100:101], 0x18a10000
	v_lshl_add_u64 v[198:199], s[42:43], 0, v[198:199]
	v_lshl_add_u64 v[198:199], v[198:199], 0, s[30:31]
	v_lshl_add_u64 v[198:199], v[198:199], 0, v[196:197]
	v_lshl_add_u64 v[198:199], v[198:199], 0, s[100:101]
	global_load_dwordx2 v[146:147], v[198:199], off
	global_load_dwordx2 v[148:149], v[198:199], off offset:32
	global_load_dwordx2 v[150:151], v[198:199], off offset:64
	global_load_dwordx2 v[152:153], v[198:199], off offset:96
	global_load_dwordx2 v[188:189], v[198:199], off offset:128
	global_load_dwordx2 v[190:191], v[198:199], off offset:160
	global_load_dwordx2 v[192:193], v[198:199], off offset:192
	global_load_dwordx2 v[194:195], v[198:199], off offset:224
	s_mov_b64 s[100:101], exec
	s_and_b64 exec, exec, s[4:5]
	s_cbranch_execz .Lpop_skip
	v_readlane_b32 s14, v255, 22
	v_readlane_b32 s15, v255, 23
	v_mov_b32_e32 v224, 1
	s_nop 4
	global_atomic_add v224, v0, v224, s[14:15] sc0
